# context-row norm phases: the 24 gain/scale/shift vector loads issued together (were 9 load groups each followed by vmcnt(0))
# speedup vs baseline: 1.0055x; 1.0055x over previous
; #define INP(i) ((const float*)TABP(i))
; #define PHASE_BEGIN() if (need_bar) xcd_barrier(bar); need_bar = true; int tid = threadIdx.x; asm volatile("" : "+v"(tid)); const int lane = tid & 63, wave = __builtin_amdgcn_readfirstlane(tid >> 6), gw = vcu * NWAVES + wave; (void)lane; (void)gw; unsigned char* const wsl = TABP(24); (void)wsl; int bxp = bx; asm volatile("" : "+s"(bxp)); (void)bxp
; #define VECS7(m) norm_vecs<0>(g2, ml + (size_t)(m) * MODW + 3 * D, ml + (size_t)(m) * MODW + 4 * D, GG, SS, lane)
; __global__ void __launch_bounds__(NTHREADS, 2) mega(Args args) {
;     ...
;             PHASE_BEGIN();
;             const float* ml = WSF(WS_MODS) + (size_t)L * 5 * MODW; bf16_t* X = WSB(WS_X); bf16_t* XN = WSB(WS_XN); const float* g2 = INP(7) + (size_t)L * D;
;             const float* slab = WSF(WS_SLAB);
;     ...
;             if (!lastL) { f32x4 GG[8], SS[8]; VECS7(4); const float* mm = ml + (size_t)4 * MODW;
;                 for (int row = ML + wave * G + bx; row < M; row += NGW)     { f32x4 v[8]; norm_load(X + (size_t)row * D, v, lane);
.LBB9_1329:
	s_waitcnt vmcnt(0)
	v_mov_b32_e32 v2, v0
	v_mov_b32_e32 v3, v241
	ds_read_b64 v[4:5], v3 offset:192
	v_readlane_b32 s1, v254, 4
	v_mov_b32_e32 v3, v241
	s_waitcnt lgkmcnt(0)
	v_readfirstlane_b32 s4, v5
	v_readfirstlane_b32 s5, v4
	ds_read_b64 v[4:5], v3 offset:56
	v_readfirstlane_b32 s0, v2
	s_ashr_i32 s1, s0, 6
	s_mul_i32 s1, s1, s95
	v_readlane_b32 s0, v254, 12
	s_add_i32 s0, s0, s1
	v_readlane_b32 s88, v255, 46
	s_mov_b32 s65, 0x380000
	s_mov_b32 s79, 0x5a0000
	s_mov_b32 s81, 0x5c0000
	s_mov_b32 s87, 0x620000
	s_mov_b32 s96, 0x640000
	s_mov_b32 s73, 0x440000
	s_mov_b32 s74, 0x680000
	s_mov_b32 s97, 0x520000
	s_mov_b32 s50, 0x720000
	s_mov_b32 s46, 0x500000
	s_mov_b32 s71, 0x6a0000
	s_mov_b32 s75, 0x5e0000
	s_mov_b32 s43, 0x4a0000
	s_mov_b32 s67, 0x7a0000
	s_mov_b32 s78, 0x400000
	s_mov_b32 s80, 0x3c0000
	s_waitcnt lgkmcnt(0)
	v_readfirstlane_b32 s10, v5
	v_readfirstlane_b32 s11, v4
	s_mov_b32 s42, s95
	s_cmpk_gt_i32 s0, 0x23ff
	s_mov_b32 s24, 0x160000
	s_mov_b32 s25, 0x240000
	s_mov_b32 s40, 0x260000
	s_mov_b32 s41, 0x280000
	s_mov_b32 s48, 0x2a0000
	s_mov_b32 s52, 0x2c0000
	s_mov_b32 s53, 0x2e0000
	s_mov_b32 s54, 0x320000
	s_mov_b32 s55, 0x560000
	s_mov_b32 s57, 0x6c0000
	s_mov_b32 s44, 0x6e0000
	s_mov_b32 s45, 0x700000
	s_mov_b32 s47, 0x740000
	v_readlane_b32 s89, v255, 47
	v_readlane_b32 s14, v255, 9
	s_mov_b32 s51, 0x760000
	s_mov_b32 s33, 0x3a0000
	s_mov_b32 s37, 0x540000
	s_mov_b32 s72, 0x7c0000
	s_mov_b32 s93, 0x1a0000
	v_readlane_b32 s92, v254, 62
	s_mov_b32 s95, 0x580000
	s_mov_b32 s76, 0x60000
	s_mov_b32 s59, 0x1e0000
	s_mov_b32 s66, 0x7e0000
	v_readlane_b32 s15, v255, 10
	s_cbranch_scc1 .LBB9_1332
; #define VECS7(m) norm_vecs<0>(g2, ml + (size_t)(m) * MODW + 3 * D, ml + (size_t)(m) * MODW + 4 * D, GG, SS, lane)
; template <int MODE>
; __device__ __forceinline__ void norm_vecs(const float* g, const float* sh, const float* sc, f32x4 (&GG)[8], f32x4 (&SS)[8], int lane) {
; #pragma unroll
;     for (int j = 0; j < 8; ++j) { GG[j] = ((const f32x4*)g)[lane + 64 * j];
;         if (MODE == 0) { GG[j] = GG[j] * (((const f32x4*)sc)[lane + 64 * j] + 1.f); SS[j] = ((const f32x4*)sh)[lane + 64 * j]; } }
; __global__ void __launch_bounds__(NTHREADS, 2) mega(Args args) {
;     ...
;             if (!lastL) { f32x4 GG[8], SS[8]; VECS7(4); const float* mm = ml + (size_t)4 * MODW;
;                 for (int row = ML + wave * G + bx; row < M; row += NGW)     { f32x4 v[8]; norm_load(X + (size_t)row * D, v, lane);
;                     norm_apply<0>(v, X + (size_t)row * D, GG, SS, XN + (size_t)row * D, nullptr, lane,
;                                   (const float*)((const bf16_t*)slab + (size_t)((row - ML) >> 8) * 64 * 65536 + (size_t)(row & 255) * 256), mm + 2 * D); } }
	v_readlane_b32 s18, v255, 50
	v_readlane_b32 s19, v255, 51
	s_add_u32 s22, s5, 0x3f100000
	s_mov_b32 s19, s49
	s_mov_b32 s82, s14
	s_addc_u32 s23, s4, 0
	s_lshl_b64 s[14:15], s[18:19], 13
	s_add_u32 s14, s11, s14
	s_addc_u32 s15, s10, s15
	s_mov_b32 s10, s18
	v_writelane_b32 v255, s10, 50
	s_mul_i32 s9, s18, 0x3c000
	s_mul_hi_u32 s3, s18, 0x3c000
	v_writelane_b32 v255, s11, 51
	s_add_u32 s10, s5, s9
	s_addc_u32 s11, s4, s3
	s_add_u32 s18, s10, 0x136000
	v_and_b32_e32 v78, 63, v2
	s_addc_u32 s19, s11, 0
	s_add_u32 s20, s10, 0x138000
	v_lshlrev_b32_e32 v186, 4, v78
	s_addc_u32 s21, s11, 0
	v_or_b32_e32 v14, 0x400, v186
	v_or_b32_e32 v18, 0x800, v186
	v_or_b32_e32 v22, 0xc00, v186
	v_or_b32_e32 v26, 0x1000, v186
	v_or_b32_e32 v30, 0x1400, v186
	v_or_b32_e32 v62, 0x1800, v186
	v_or_b32_e32 v68, 0x1c00, v186
	global_load_dwordx4 v[80:83], v186, s[14:15]
	global_load_dwordx4 v[84:87], v186, s[20:21]
	global_load_dwordx4 v[2:5], v186, s[18:19]
	global_load_dwordx4 v[88:91], v186, s[14:15] offset:1024
	global_load_dwordx4 v[92:95], v14, s[20:21]
	global_load_dwordx4 v[6:9], v14, s[18:19]
	global_load_dwordx4 v[96:99], v186, s[14:15] offset:2048
	global_load_dwordx4 v[100:103], v18, s[20:21]
	global_load_dwordx4 v[10:13], v18, s[18:19]
	global_load_dwordx4 v[104:107], v186, s[14:15] offset:3072
	global_load_dwordx4 v[108:111], v22, s[20:21]
	global_load_dwordx4 v[14:17], v22, s[18:19]
	global_load_dwordx4 v[112:115], v26, s[14:15]
	global_load_dwordx4 v[116:119], v26, s[20:21]
	global_load_dwordx4 v[18:21], v26, s[18:19]
	global_load_dwordx4 v[120:123], v30, s[14:15]
	global_load_dwordx4 v[124:127], v30, s[20:21]
	global_load_dwordx4 v[22:25], v30, s[18:19]
	global_load_dwordx4 v[128:131], v62, s[14:15]
	global_load_dwordx4 v[132:135], v62, s[20:21]
	global_load_dwordx4 v[26:29], v62, s[18:19]
	global_load_dwordx4 v[136:139], v68, s[14:15]
	global_load_dwordx4 v[140:143], v68, s[20:21]
	global_load_dwordx4 v[30:33], v68, s[18:19]
	v_and_b32_e32 v76, 64, v242
	v_add_u32_e32 v76, 64, v76
	v_xor_b32_e32 v77, 1, v242
	v_cmp_lt_i32_e32 vcc, v77, v76
	v_lshl_add_u64 v[74:75], s[10:11], 0, v[186:187]
	s_mov_b64 s[10:11], 0x134000
	v_cndmask_b32_e32 v77, v242, v77, vcc
	v_lshlrev_b32_e32 v178, 2, v77
	v_xor_b32_e32 v77, 2, v242
	v_cmp_lt_i32_e32 vcc, v77, v76
	v_readlane_b32 s3, v254, 4
	s_waitcnt vmcnt(22)
	v_pk_add_f32 v[86:87], v[86:87], 1.0 op_sel_hi:[1,0]
	v_pk_add_f32 v[84:85], v[84:85], 1.0 op_sel_hi:[1,0]
	v_pk_mul_f32 v[34:35], v[82:83], v[86:87]
	v_pk_mul_f32 v[36:37], v[80:81], v[84:85]
	v_cndmask_b32_e32 v77, v242, v77, vcc
	v_lshlrev_b32_e32 v179, 2, v77
	v_xor_b32_e32 v77, 4, v242
	v_cmp_lt_i32_e32 vcc, v77, v76
	s_waitcnt vmcnt(19)
	v_pk_add_f32 v[94:95], v[94:95], 1.0 op_sel_hi:[1,0]
	v_pk_add_f32 v[92:93], v[92:93], 1.0 op_sel_hi:[1,0]
	v_pk_mul_f32 v[38:39], v[90:91], v[94:95]
	v_pk_mul_f32 v[40:41], v[88:89], v[92:93]
	v_cndmask_b32_e32 v77, v242, v77, vcc
	v_lshlrev_b32_e32 v180, 2, v77
	v_xor_b32_e32 v77, 8, v242
	v_cmp_lt_i32_e32 vcc, v77, v76
	s_waitcnt vmcnt(16)
	v_pk_add_f32 v[102:103], v[102:103], 1.0 op_sel_hi:[1,0]
	v_pk_add_f32 v[100:101], v[100:101], 1.0 op_sel_hi:[1,0]
	v_pk_mul_f32 v[42:43], v[98:99], v[102:103]
	v_pk_mul_f32 v[44:45], v[96:97], v[100:101]
	v_cndmask_b32_e32 v77, v242, v77, vcc
	v_lshlrev_b32_e32 v181, 2, v77
	v_xor_b32_e32 v77, 16, v242
	v_cmp_lt_i32_e32 vcc, v77, v76
	v_lshlrev_b32_e32 v186, 3, v78
	s_waitcnt vmcnt(13)
	v_pk_add_f32 v[110:111], v[110:111], 1.0 op_sel_hi:[1,0]
	v_pk_add_f32 v[108:109], v[108:109], 1.0 op_sel_hi:[1,0]
	v_pk_mul_f32 v[46:47], v[106:107], v[110:111]
	v_pk_mul_f32 v[48:49], v[104:105], v[108:109]
	v_cndmask_b32_e32 v77, v242, v77, vcc
	v_lshlrev_b32_e32 v182, 2, v77
	v_xor_b32_e32 v77, 32, v242
	v_cmp_lt_i32_e32 vcc, v77, v76
	s_waitcnt vmcnt(10)
	v_pk_add_f32 v[118:119], v[118:119], 1.0 op_sel_hi:[1,0]
	v_pk_add_f32 v[116:117], v[116:117], 1.0 op_sel_hi:[1,0]
	v_pk_mul_f32 v[50:51], v[114:115], v[118:119]
	v_pk_mul_f32 v[52:53], v[112:113], v[116:117]
	v_cndmask_b32_e32 v76, v242, v77, vcc
	v_lshlrev_b32_e32 v183, 2, v76
	s_waitcnt vmcnt(7)
	v_pk_add_f32 v[126:127], v[126:127], 1.0 op_sel_hi:[1,0]
	v_pk_add_f32 v[124:125], v[124:125], 1.0 op_sel_hi:[1,0]
	v_pk_mul_f32 v[54:55], v[122:123], v[126:127]
	v_pk_mul_f32 v[56:57], v[120:121], v[124:125]
	s_waitcnt vmcnt(4)
	v_pk_add_f32 v[134:135], v[134:135], 1.0 op_sel_hi:[1,0]
	v_pk_add_f32 v[132:133], v[132:133], 1.0 op_sel_hi:[1,0]
	v_pk_mul_f32 v[58:59], v[130:131], v[134:135]
	v_pk_mul_f32 v[60:61], v[128:129], v[132:133]
	s_waitcnt vmcnt(1)
	v_pk_add_f32 v[142:143], v[142:143], 1.0 op_sel_hi:[1,0]
	v_pk_add_f32 v[66:67], v[140:141], 1.0 op_sel_hi:[1,0]
	v_pk_mul_f32 v[62:63], v[138:139], v[142:143]
	v_pk_mul_f32 v[64:65], v[136:137], v[66:67]
	v_lshl_add_u64 v[66:67], v[74:75], 0, s[10:11]
	s_mov_b64 s[10:11], 0x135000
	v_lshl_add_u64 v[68:69], v[74:75], 0, s[10:11]
	s_mov_b64 s[10:11], 0x135400
	v_lshl_add_u64 v[70:71], v[74:75], 0, s[10:11]
	s_mov_b64 s[10:11], 0x135800
	v_lshl_add_u64 v[72:73], v[74:75], 0, s[10:11]
	s_mov_b64 s[10:11], 0x135c00
	v_lshl_add_u64 v[74:75], v[74:75], 0, s[10:11]
	s_add_i32 s10, s3, s1
	s_ashr_i32 s1, s0, 31
	s_lshl_b64 s[14:15], s[0:1], 12
	s_add_u32 s14, s5, s14
	s_addc_u32 s15, s4, s15
	v_lshl_add_u64 v[76:77], s[14:15], 0, v[186:187]
	s_mov_b64 s[4:5], 0x1d700e00
	v_lshl_add_u64 v[76:77], v[76:77], 0, s[4:5]
	s_lshl_b32 s0, s0, 8
	v_lshlrev_b32_e32 v186, 3, v78

; #define INP(i) ((const float*)TABP(i))
; #define PHASE_BEGIN() if (need_bar) xcd_barrier(bar); need_bar = true; int tid = threadIdx.x; asm volatile("" : "+v"(tid)); const int lane = tid & 63, wave = __builtin_amdgcn_readfirstlane(tid >> 6), gw = vcu * NWAVES + wave; (void)lane; (void)gw; unsigned char* const wsl = TABP(24); (void)wsl; int bxp = bx; asm volatile("" : "+s"(bxp)); (void)bxp
; #define VECS10B(m) norm_vecs<0>(g1n, mn + (size_t)(m) * MODW, mn + (size_t)(m) * MODW + D, GG, SS, lane)
; __global__ void __launch_bounds__(NTHREADS, 2) mega(Args args) {
;     ...
;         if (IN(base + 10) && !lastL) {
;             PHASE_BEGIN();
;             bf16_t* X = WSB(WS_X);
;     ...
;             { const float* mn = WSF(WS_MODS) + (size_t)(L + 1) * 5 * MODW; bf16_t* XN = WSB(WS_XN); const float* g1n = INP(6) + (size_t)(L + 1) * D;
;                 const float* slab = WSF(WS_SLAB); const float* gate5 = WSF(WS_MODS) + ((size_t)L * 5 + 4) * MODW + 5 * D;
;     ...
;                 { f32x4 GG[8], SS[8]; VECS10B(4);
;                   for (int row = ML + wave * G + bx; row < M; row += NGW)     { f32x4 v[8]; norm_load(X + (size_t)row * D, v, lane);
.LBB9_1722:
	s_waitcnt vmcnt(0)
	v_mov_b32_e32 v2, v0
	v_mov_b32_e32 v3, v241
	ds_read_b64 v[4:5], v3 offset:192
	v_readfirstlane_b32 s3, v2
	s_ashr_i32 s11, s3, 6
	v_readlane_b32 s3, v254, 4
	v_mov_b32_e32 v3, v241
	s_waitcnt lgkmcnt(0)
	v_readfirstlane_b32 s4, v5
	v_readfirstlane_b32 s5, v4
	ds_read_b64 v[4:5], v3 offset:48
	v_readlane_b32 s14, v255, 50
	s_mul_i32 s11, s11, s95
	v_readlane_b32 s3, v254, 12
	v_readlane_b32 s84, v255, 9
	v_readlane_b32 s15, v255, 51
	s_add_i32 s48, s14, 1
	s_add_i32 s10, s3, s11
	v_readlane_b32 s90, v255, 46
	v_readlane_b32 s85, v255, 10
	s_waitcnt lgkmcnt(0)
	v_readfirstlane_b32 s14, v5
	v_readfirstlane_b32 s15, v4
	s_mov_b32 s73, 0x6a0000
	s_mov_b32 s97, 0x680000
	s_mov_b32 s87, 0x640000
	s_cmpk_gt_i32 s10, 0x23ff
	s_mov_b32 s16, 0x300000
	s_mov_b32 s30, 0x360000
	s_mov_b32 s31, 0x480000
	s_mov_b32 s34, 0x4e0000
	s_mov_b32 s35, 0x600000
	s_mov_b32 s40, 0x660000
	s_mov_b32 s41, 0x780000
	s_mov_b32 s52, 0x160000
	s_mov_b32 s53, 0x240000
	s_mov_b32 s54, 0x260000
	s_mov_b32 s55, 0x280000
	s_mov_b32 s57, 0x2a0000
	s_mov_b32 s65, 0x2c0000
	s_mov_b32 s37, 0xa0000
	s_mov_b32 s93, 0x460000
	s_mov_b32 s83, 0x2e0000
	s_mov_b32 s72, 0x520000
	s_mov_b32 s96, 0x4c0000
	s_mov_b32 s89, 0x4a0000
	s_mov_b32 s88, 0x440000
	s_mov_b32 s74, 0x400000
	s_mov_b32 s80, 0x3c0000
	s_mov_b32 s78, 0x380000
	s_mov_b32 s76, 0x320000
	s_mov_b32 s95, 0x620000
	s_mov_b32 s75, 0x5e0000
	s_mov_b32 s81, 0x5c0000
	s_mov_b32 s79, 0x5a0000
	s_mov_b32 s77, 0x560000
	s_mov_b32 s44, 0x6c0000
	s_mov_b32 s45, 0x6e0000
	s_mov_b32 s47, 0x720000
	s_mov_b32 s46, 0x700000
	s_mov_b32 s36, 0x7a0000
	s_mov_b32 s92, 0x740000
	s_mov_b32 s1, 0x760000
	s_mov_b32 s82, 0xe0000
	v_readlane_b32 s91, v255, 47
	s_mov_b32 s33, 0x340000
	s_mov_b32 s70, 0x120000
	s_mov_b32 s68, 0x420000
	s_mov_b32 s94, 0x3e0000
	s_mov_b32 s51, 0x20000
	s_mov_b32 s56, 0x800000
	s_mov_b32 s85, 0x3a0000
	s_mov_b32 s0, 0x200000
	s_mov_b32 s86, 0x500000
	s_mov_b32 s71, 0x540000
	s_mov_b32 s50, 0x7c0000
	s_mov_b32 s43, 0x1a0000
	v_readlane_b32 s67, v254, 62
	s_mov_b32 s42, 0x580000
	s_mov_b32 s59, 0x60000
	s_mov_b32 s66, 0x1e0000
	s_mov_b32 s63, 0x7e0000
	s_cbranch_scc1 .LBB9_1725
; #define VECS10B(m) norm_vecs<0>(g1n, mn + (size_t)(m) * MODW, mn + (size_t)(m) * MODW + D, GG, SS, lane)
; template <int MODE>
; __device__ __forceinline__ void norm_vecs(const float* g, const float* sh, const float* sc, f32x4 (&GG)[8], f32x4 (&SS)[8], int lane) {
; #pragma unroll
;     for (int j = 0; j < 8; ++j) { GG[j] = ((const f32x4*)g)[lane + 64 * j];
;         if (MODE == 0) { GG[j] = GG[j] * (((const f32x4*)sc)[lane + 64 * j] + 1.f); SS[j] = ((const f32x4*)sh)[lane + 64 * j]; } }
; __global__ void __launch_bounds__(NTHREADS, 2) mega(Args args) {
;     ...
;                 { f32x4 GG[8], SS[8]; VECS10B(4);
;                   for (int row = ML + wave * G + bx; row < M; row += NGW)     { f32x4 v[8]; norm_load(X + (size_t)row * D, v, lane);
;                       norm_apply<0>(v, X + (size_t)row * D, GG, SS, XN + (size_t)row * D, nullptr, lane,
;                                     (const float*)((const bf16_t*)slab + (size_t)((row - ML) >> 8) * 64 * 65536 + (size_t)(row & 255) * 256), gate5); } }
	s_add_u32 s24, s5, 0x100000
	s_addc_u32 s25, s4, 0
	s_mul_i32 s9, s48, 0x3c000
	s_mul_hi_u32 s3, s48, 0x3c000
	s_add_u32 s9, s24, s9
	s_addc_u32 s3, s25, s3
	s_lshl_b64 s[18:19], s[48:49], 13
	s_add_u32 s18, s15, s18
	s_addc_u32 s19, s14, s19
	s_add_u32 s22, s5, 0x3f100000
	s_addc_u32 s23, s4, 0
	s_add_u32 s14, s9, 0x30000
	v_and_b32_e32 v78, 63, v2
	s_addc_u32 s15, s3, 0
	s_add_u32 s20, s9, 0x32000
	v_lshlrev_b32_e32 v186, 4, v78
	s_addc_u32 s21, s3, 0
	v_or_b32_e32 v14, 0x400, v186
	v_or_b32_e32 v18, 0x800, v186
	v_or_b32_e32 v22, 0xc00, v186
	v_or_b32_e32 v26, 0x1000, v186
	v_or_b32_e32 v30, 0x1400, v186
	v_or_b32_e32 v62, 0x1800, v186
	v_or_b32_e32 v68, 0x1c00, v186
	global_load_dwordx4 v[80:83], v186, s[18:19]
	global_load_dwordx4 v[84:87], v186, s[20:21]
	global_load_dwordx4 v[2:5], v186, s[14:15]
	global_load_dwordx4 v[88:91], v186, s[18:19] offset:1024
	global_load_dwordx4 v[92:95], v14, s[20:21]
	global_load_dwordx4 v[6:9], v14, s[14:15]
	global_load_dwordx4 v[96:99], v186, s[18:19] offset:2048
	global_load_dwordx4 v[100:103], v18, s[20:21]
	global_load_dwordx4 v[10:13], v18, s[14:15]
	global_load_dwordx4 v[104:107], v186, s[18:19] offset:3072
	global_load_dwordx4 v[108:111], v22, s[20:21]
	global_load_dwordx4 v[14:17], v22, s[14:15]
	global_load_dwordx4 v[112:115], v26, s[18:19]
	global_load_dwordx4 v[116:119], v26, s[20:21]
	global_load_dwordx4 v[18:21], v26, s[14:15]
	global_load_dwordx4 v[120:123], v30, s[18:19]
	global_load_dwordx4 v[124:127], v30, s[20:21]
	global_load_dwordx4 v[22:25], v30, s[14:15]
	global_load_dwordx4 v[128:131], v62, s[18:19]
	global_load_dwordx4 v[132:135], v62, s[20:21]
	global_load_dwordx4 v[26:29], v62, s[14:15]
	global_load_dwordx4 v[136:139], v68, s[18:19]
	global_load_dwordx4 v[140:143], v68, s[20:21]
	global_load_dwordx4 v[30:33], v68, s[14:15]
	v_and_b32_e32 v76, 64, v242
	v_add_u32_e32 v76, 64, v76
	v_xor_b32_e32 v77, 1, v242
	v_cmp_lt_i32_e32 vcc, v77, v76
	v_readlane_b32 s3, v254, 4
	s_waitcnt vmcnt(22)
	v_pk_add_f32 v[86:87], v[86:87], 1.0 op_sel_hi:[1,0]
	v_pk_add_f32 v[84:85], v[84:85], 1.0 op_sel_hi:[1,0]
	v_pk_mul_f32 v[34:35], v[82:83], v[86:87]
	v_pk_mul_f32 v[36:37], v[80:81], v[84:85]
	v_cndmask_b32_e32 v77, v242, v77, vcc
	v_lshlrev_b32_e32 v178, 2, v77
	v_xor_b32_e32 v77, 2, v242
	v_cmp_lt_i32_e32 vcc, v77, v76
	s_waitcnt vmcnt(19)
	v_pk_add_f32 v[94:95], v[94:95], 1.0 op_sel_hi:[1,0]
	v_pk_add_f32 v[92:93], v[92:93], 1.0 op_sel_hi:[1,0]
	v_pk_mul_f32 v[38:39], v[90:91], v[94:95]
	v_pk_mul_f32 v[40:41], v[88:89], v[92:93]
	v_cndmask_b32_e32 v77, v242, v77, vcc
	v_lshlrev_b32_e32 v179, 2, v77
	v_xor_b32_e32 v77, 4, v242
	v_cmp_lt_i32_e32 vcc, v77, v76
	s_waitcnt vmcnt(16)
	v_pk_add_f32 v[102:103], v[102:103], 1.0 op_sel_hi:[1,0]
	v_pk_add_f32 v[100:101], v[100:101], 1.0 op_sel_hi:[1,0]
	v_pk_mul_f32 v[42:43], v[98:99], v[102:103]
	v_pk_mul_f32 v[44:45], v[96:97], v[100:101]
	v_cndmask_b32_e32 v77, v242, v77, vcc
	v_lshlrev_b32_e32 v180, 2, v77
	v_xor_b32_e32 v77, 8, v242
	v_cmp_lt_i32_e32 vcc, v77, v76
	s_waitcnt vmcnt(13)
	v_pk_add_f32 v[110:111], v[110:111], 1.0 op_sel_hi:[1,0]
	v_pk_add_f32 v[108:109], v[108:109], 1.0 op_sel_hi:[1,0]
	v_pk_mul_f32 v[46:47], v[106:107], v[110:111]
	v_pk_mul_f32 v[48:49], v[104:105], v[108:109]
	v_cndmask_b32_e32 v77, v242, v77, vcc
	v_lshlrev_b32_e32 v181, 2, v77
	v_xor_b32_e32 v77, 16, v242
	v_cmp_lt_i32_e32 vcc, v77, v76
	s_waitcnt vmcnt(10)
	v_pk_add_f32 v[118:119], v[118:119], 1.0 op_sel_hi:[1,0]
	v_pk_add_f32 v[116:117], v[116:117], 1.0 op_sel_hi:[1,0]
	v_pk_mul_f32 v[50:51], v[114:115], v[118:119]
	v_pk_mul_f32 v[52:53], v[112:113], v[116:117]
	v_cndmask_b32_e32 v77, v242, v77, vcc
	v_lshlrev_b32_e32 v182, 2, v77
	v_xor_b32_e32 v77, 32, v242
	v_cmp_lt_i32_e32 vcc, v77, v76
	s_waitcnt vmcnt(7)
	v_pk_add_f32 v[126:127], v[126:127], 1.0 op_sel_hi:[1,0]
	v_pk_add_f32 v[124:125], v[124:125], 1.0 op_sel_hi:[1,0]
	v_pk_mul_f32 v[54:55], v[122:123], v[126:127]
	v_pk_mul_f32 v[56:57], v[120:121], v[124:125]
	v_cndmask_b32_e32 v76, v242, v77, vcc
	v_lshlrev_b32_e32 v183, 2, v76
	s_waitcnt vmcnt(4)
	v_pk_add_f32 v[134:135], v[134:135], 1.0 op_sel_hi:[1,0]
	v_pk_add_f32 v[132:133], v[132:133], 1.0 op_sel_hi:[1,0]
	v_pk_mul_f32 v[58:59], v[130:131], v[134:135]
	v_pk_mul_f32 v[60:61], v[128:129], v[132:133]
	s_waitcnt vmcnt(1)
	v_pk_add_f32 v[142:143], v[142:143], 1.0 op_sel_hi:[1,0]
	v_pk_add_f32 v[66:67], v[140:141], 1.0 op_sel_hi:[1,0]
	v_pk_mul_f32 v[62:63], v[138:139], v[142:143]
	v_pk_mul_f32 v[64:65], v[136:137], v[66:67]
	v_readlane_b32 s14, v255, 50
	v_readlane_b32 s15, v255, 51
	s_mul_i32 s14, s14, 0xf000
	s_mov_b32 s15, s49
	s_lshl_b64 s[14:15], s[14:15], 2
	s_add_u32 s14, s24, s14
	s_addc_u32 s15, s25, s15
	v_lshl_add_u64 v[74:75], s[14:15], 0, v[186:187]
	s_mov_b64 s[14:15], 0x3a000
	v_lshl_add_u64 v[66:67], v[74:75], 0, s[14:15]
	s_mov_b64 s[14:15], 0x3b000
	v_lshl_add_u64 v[68:69], v[74:75], 0, s[14:15]
	s_mov_b64 s[14:15], 0x3b400
	v_lshl_add_u64 v[70:71], v[74:75], 0, s[14:15]
	s_mov_b64 s[14:15], 0x3b800
	v_lshl_add_u64 v[72:73], v[74:75], 0, s[14:15]
	s_mov_b64 s[14:15], 0x3bc00
	v_lshl_add_u64 v[74:75], v[74:75], 0, s[14:15]
	s_add_i32 s14, s3, s11
	s_ashr_i32 s11, s10, 31
	s_lshl_b64 s[18:19], s[10:11], 12
	s_add_u32 s18, s5, s18
	v_lshlrev_b32_e32 v186, 3, v78
	s_addc_u32 s19, s4, s19
	v_lshl_add_u64 v[76:77], s[18:19], 0, v[186:187]
	s_mov_b64 s[4:5], 0x1d700e00
	v_lshl_add_u64 v[76:77], v[76:77], 0, s[4:5]
	s_lshl_b32 s10, s10, 8
	v_lshlrev_b32_e32 v186, 3, v78
